# redundant s_waitcnt lgkmcnt(0) at the head of each MFMA segment removed (same wait already executed before the preceding barrier)
# baseline (speedup 1.0000x reference)
.Lpeel_join375_1:
	s_waitcnt lgkmcnt(0)
	s_barrier
	v_mfma_f32_16x16x32_bf16 v[120:123], v[128:131], v[178:181], 0
	v_mfma_f32_16x16x32_bf16 v[124:127], v[136:139], v[178:181], 0
	v_mfma_f32_16x16x32_bf16 v[100:103], v[128:131], v[206:209], 0
	v_mfma_f32_16x16x32_bf16 v[96:99], v[136:139], v[206:209], 0
	v_mfma_f32_16x16x32_bf16 v[84:87], v[128:131], v[214:217], 0
	v_mfma_f32_16x16x32_bf16 v[80:83], v[136:139], v[214:217], 0
	v_mfma_f32_16x16x32_bf16 v[68:71], v[128:131], v[222:225], 0
	v_mfma_f32_16x16x32_bf16 v[64:67], v[136:139], v[222:225], 0
	v_mfma_f32_16x16x32_bf16 v[120:123], v[132:135], v[202:205], v[120:123]
	v_mfma_f32_16x16x32_bf16 v[124:127], v[140:143], v[202:205], v[124:127]
	v_mfma_f32_16x16x32_bf16 v[100:103], v[132:135], v[210:213], v[100:103]
	v_mfma_f32_16x16x32_bf16 v[96:99], v[140:143], v[210:213], v[96:99]
	v_mfma_f32_16x16x32_bf16 v[84:87], v[132:135], v[218:221], v[84:87]
	v_mfma_f32_16x16x32_bf16 v[80:83], v[140:143], v[218:221], v[80:83]
	v_mfma_f32_16x16x32_bf16 v[68:71], v[132:135], v[226:229], v[68:71]
	v_mfma_f32_16x16x32_bf16 v[64:67], v[140:143], v[226:229], v[64:67]
	v_mfma_f32_16x16x32_bf16 v[116:119], v[144:147], v[178:181], 0
	v_mfma_f32_16x16x32_bf16 v[112:115], v[170:173], v[178:181], 0
	v_mfma_f32_16x16x32_bf16 v[108:111], v[144:147], v[206:209], 0
	v_mfma_f32_16x16x32_bf16 v[104:107], v[170:173], v[206:209], 0
	v_mfma_f32_16x16x32_bf16 v[92:95], v[144:147], v[214:217], 0
	v_mfma_f32_16x16x32_bf16 v[88:91], v[170:173], v[214:217], 0
	v_mfma_f32_16x16x32_bf16 v[76:79], v[144:147], v[222:225], 0
	v_mfma_f32_16x16x32_bf16 v[72:75], v[170:173], v[222:225], 0
	v_mfma_f32_16x16x32_bf16 v[116:119], v[148:151], v[202:205], v[116:119]
	v_mfma_f32_16x16x32_bf16 v[112:115], v[174:177], v[202:205], v[112:115]
	v_mfma_f32_16x16x32_bf16 v[108:111], v[148:151], v[210:213], v[108:111]
	v_mfma_f32_16x16x32_bf16 v[104:107], v[174:177], v[210:213], v[104:107]
	v_mfma_f32_16x16x32_bf16 v[92:95], v[148:151], v[218:221], v[92:95]
	v_mfma_f32_16x16x32_bf16 v[88:91], v[174:177], v[218:221], v[88:91]
	v_mfma_f32_16x16x32_bf16 v[76:79], v[148:151], v[226:229], v[76:79]
	v_mfma_f32_16x16x32_bf16 v[72:75], v[174:177], v[226:229], v[72:75]
	s_barrier
	s_add_i32 s12, s12, s17
	v_lshl_add_u64 v[230:231], s[14:15], 0, v[154:155]
	s_mov_b32 m0, s12
	ds_read_b128 v[178:181], v157 offset:16384
	ds_read_b128 v[202:205], v157 offset:17408
	ds_read_b128 v[206:209], v157 offset:18432
	ds_read_b128 v[210:213], v157 offset:19456
	ds_read_b128 v[214:217], v157 offset:20480
	ds_read_b128 v[218:221], v157 offset:21504
	ds_read_b128 v[222:225], v157 offset:22528
	ds_read_b128 v[226:229], v157 offset:23552
	global_load_lds_dwordx4 v[230:231], off
	s_add_i32 m0, s12, 0x2000
	v_lshl_add_u64 v[232:233], s[14:15], 0, v[162:163]
	s_add_u32 s14, s14, s24
	s_addc_u32 s15, s15, s25
	s_add_i32 s2, s2, s17
	global_load_lds_dwordx4 v[232:233], off
	v_lshl_add_u64 v[234:235], s[14:15], 0, v[154:155]
	s_mov_b32 m0, s2
	v_lshl_add_u64 v[236:237], s[14:15], 0, v[162:163]
	global_load_lds_dwordx4 v[234:235], off
	s_add_i32 m0, s2, 0x2000
	v_lshl_add_u64 v[238:239], s[0:1], 0, v[158:159]
	global_load_lds_dwordx4 v[236:237], off
	s_mov_b32 m0, s45
	v_lshl_add_u64 v[240:241], s[0:1], 0, v[160:161]
	global_load_lds_dwordx4 v[238:239], off
	s_mov_b32 m0, s83
	s_nop 0
	global_load_lds_dwordx4 v[240:241], off
	s_lshl_b32 s99, s17, 1
	s_add_i32 m0, s99, 0x20000
	s_lshl_b32 s98, s65, 14
	s_add_i32 s98, s98, s99
	s_add_u32 s98, s100, s98
	s_addc_u32 s99, s101, 0
	global_load_lds_dwordx4 v248, s[98:99]
	global_load_lds_dwordx4 v248, s[98:99] offset:1024
	s_cmp_eq_u32 s18, 1
	s_cbranch_scc1 .Lpeel_strict375_2
	s_waitcnt vmcnt(18)
	s_branch .Lpeel_join375_2

.Lpeel_join375_2:
	s_waitcnt lgkmcnt(0)
	s_barrier
	v_mfma_f32_16x16x32_bf16 v[52:55], v[128:131], v[178:181], 0
	v_mfma_f32_16x16x32_bf16 v[48:51], v[136:139], v[178:181], 0
	v_mfma_f32_16x16x32_bf16 v[36:39], v[128:131], v[206:209], 0
	v_mfma_f32_16x16x32_bf16 v[32:35], v[136:139], v[206:209], 0
	v_mfma_f32_16x16x32_bf16 v[20:23], v[128:131], v[214:217], 0
	v_mfma_f32_16x16x32_bf16 v[16:19], v[136:139], v[214:217], 0
	v_mfma_f32_16x16x32_bf16 v[4:7], v[128:131], v[222:225], 0
	v_mfma_f32_16x16x32_bf16 v[0:3], v[136:139], v[222:225], 0
	v_mfma_f32_16x16x32_bf16 v[52:55], v[132:135], v[202:205], v[52:55]
	v_mfma_f32_16x16x32_bf16 v[48:51], v[140:143], v[202:205], v[48:51]
	v_mfma_f32_16x16x32_bf16 v[36:39], v[132:135], v[210:213], v[36:39]
	v_mfma_f32_16x16x32_bf16 v[32:35], v[140:143], v[210:213], v[32:35]
	v_mfma_f32_16x16x32_bf16 v[20:23], v[132:135], v[218:221], v[20:23]
	v_mfma_f32_16x16x32_bf16 v[16:19], v[140:143], v[218:221], v[16:19]
	v_mfma_f32_16x16x32_bf16 v[4:7], v[132:135], v[226:229], v[4:7]
	v_mfma_f32_16x16x32_bf16 v[0:3], v[140:143], v[226:229], v[0:3]
	v_mfma_f32_16x16x32_bf16 v[60:63], v[144:147], v[178:181], 0
	v_mfma_f32_16x16x32_bf16 v[56:59], v[170:173], v[178:181], 0
	v_mfma_f32_16x16x32_bf16 v[44:47], v[144:147], v[206:209], 0
	v_mfma_f32_16x16x32_bf16 v[40:43], v[170:173], v[206:209], 0
	v_mfma_f32_16x16x32_bf16 v[28:31], v[144:147], v[214:217], 0
	v_mfma_f32_16x16x32_bf16 v[24:27], v[170:173], v[214:217], 0
	v_mfma_f32_16x16x32_bf16 v[12:15], v[144:147], v[222:225], 0
	v_mfma_f32_16x16x32_bf16 v[8:11], v[170:173], v[222:225], 0
	v_mfma_f32_16x16x32_bf16 v[60:63], v[148:151], v[202:205], v[60:63]
	v_mfma_f32_16x16x32_bf16 v[56:59], v[174:177], v[202:205], v[56:59]
	v_mfma_f32_16x16x32_bf16 v[44:47], v[148:151], v[210:213], v[44:47]
	v_mfma_f32_16x16x32_bf16 v[40:43], v[174:177], v[210:213], v[40:43]
	v_mfma_f32_16x16x32_bf16 v[28:31], v[148:151], v[218:221], v[28:31]
	v_mfma_f32_16x16x32_bf16 v[24:27], v[174:177], v[218:221], v[24:27]
	v_mfma_f32_16x16x32_bf16 v[12:15], v[148:151], v[226:229], v[12:15]
	v_mfma_f32_16x16x32_bf16 v[8:11], v[174:177], v[226:229], v[8:11]
	s_barrier
	s_add_i32 s2, 0, 0x18000
	s_add_i32 s12, 0, 0x1c000
	v_add_u32_e32 v140, s2, v195
	v_add_u32_e32 v174, s12, v195
	ds_read_b128 v[128:131], v140
	ds_read_b128 v[132:135], v140 offset:1024
	ds_read_b128 v[136:139], v140 offset:2048
	ds_read_b128 v[140:143], v140 offset:3072
	ds_read_b128 v[144:147], v174
	ds_read_b128 v[148:151], v174 offset:1024
	ds_read_b128 v[170:173], v174 offset:2048
	ds_read_b128 v[174:177], v174 offset:3072
	s_add_u32 s0, s0, s8
	s_addc_u32 s1, s1, s9
	s_mov_b32 m0, s28
	v_lshl_add_u64 v[242:243], s[0:1], 0, v[158:159]
	ds_read_b128 v[178:181], v157 offset:32768
	ds_read_b128 v[202:205], v157 offset:33792
	ds_read_b128 v[206:209], v157 offset:34816
	ds_read_b128 v[210:213], v157 offset:35840
	ds_read_b128 v[214:217], v157 offset:36864
	ds_read_b128 v[218:221], v157 offset:37888
	ds_read_b128 v[222:225], v157 offset:38912
	ds_read_b128 v[226:229], v157 offset:39936
	global_load_lds_dwordx4 v[242:243], off
	v_lshl_add_u64 v[242:243], s[0:1], 0, v[160:161]
	s_mov_b32 m0, s29
	s_nop 0
	global_load_lds_dwordx4 v[242:243], off
	s_waitcnt vmcnt(10)
	s_waitcnt lgkmcnt(0)
	s_barrier
	v_mfma_f32_16x16x32_bf16 v[120:123], v[128:131], v[178:181], v[120:123]
	v_mfma_f32_16x16x32_bf16 v[124:127], v[136:139], v[178:181], v[124:127]
	v_mfma_f32_16x16x32_bf16 v[100:103], v[128:131], v[206:209], v[100:103]
	v_mfma_f32_16x16x32_bf16 v[96:99], v[136:139], v[206:209], v[96:99]
	v_mfma_f32_16x16x32_bf16 v[84:87], v[128:131], v[214:217], v[84:87]
	v_mfma_f32_16x16x32_bf16 v[80:83], v[136:139], v[214:217], v[80:83]
	v_mfma_f32_16x16x32_bf16 v[68:71], v[128:131], v[222:225], v[68:71]
	v_mfma_f32_16x16x32_bf16 v[64:67], v[136:139], v[222:225], v[64:67]
	v_mfma_f32_16x16x32_bf16 v[120:123], v[132:135], v[202:205], v[120:123]
	v_mfma_f32_16x16x32_bf16 v[124:127], v[140:143], v[202:205], v[124:127]
	v_mfma_f32_16x16x32_bf16 v[100:103], v[132:135], v[210:213], v[100:103]
	v_mfma_f32_16x16x32_bf16 v[96:99], v[140:143], v[210:213], v[96:99]
	v_mfma_f32_16x16x32_bf16 v[84:87], v[132:135], v[218:221], v[84:87]
	v_mfma_f32_16x16x32_bf16 v[80:83], v[140:143], v[218:221], v[80:83]
	v_mfma_f32_16x16x32_bf16 v[68:71], v[132:135], v[226:229], v[68:71]
	v_mfma_f32_16x16x32_bf16 v[64:67], v[140:143], v[226:229], v[64:67]
	v_mfma_f32_16x16x32_bf16 v[116:119], v[144:147], v[178:181], v[116:119]
	v_mfma_f32_16x16x32_bf16 v[112:115], v[170:173], v[178:181], v[112:115]
	v_mfma_f32_16x16x32_bf16 v[108:111], v[144:147], v[206:209], v[108:111]
	v_mfma_f32_16x16x32_bf16 v[104:107], v[170:173], v[206:209], v[104:107]
	v_mfma_f32_16x16x32_bf16 v[92:95], v[144:147], v[214:217], v[92:95]
	v_mfma_f32_16x16x32_bf16 v[88:91], v[170:173], v[214:217], v[88:91]
	v_mfma_f32_16x16x32_bf16 v[76:79], v[144:147], v[222:225], v[76:79]
	v_mfma_f32_16x16x32_bf16 v[72:75], v[170:173], v[222:225], v[72:75]
	v_mfma_f32_16x16x32_bf16 v[116:119], v[148:151], v[202:205], v[116:119]
	v_mfma_f32_16x16x32_bf16 v[112:115], v[174:177], v[202:205], v[112:115]
	v_mfma_f32_16x16x32_bf16 v[108:111], v[148:151], v[210:213], v[108:111]
	v_mfma_f32_16x16x32_bf16 v[104:107], v[174:177], v[210:213], v[104:107]
	v_mfma_f32_16x16x32_bf16 v[92:95], v[148:151], v[218:221], v[92:95]
	v_mfma_f32_16x16x32_bf16 v[88:91], v[174:177], v[218:221], v[88:91]
	v_mfma_f32_16x16x32_bf16 v[76:79], v[148:151], v[226:229], v[76:79]
	v_mfma_f32_16x16x32_bf16 v[72:75], v[174:177], v[226:229], v[72:75]
	s_barrier
	s_add_i32 s0, s2, s17
	v_lshl_add_u64 v[230:231], v[230:231], 0, s[36:37]
	s_mov_b32 m0, s0
	ds_read_b128 v[178:181], v157 offset:49152
	ds_read_b128 v[202:205], v157 offset:50176
	ds_read_b128 v[206:209], v157 offset:51200
	ds_read_b128 v[210:213], v157 offset:52224
	ds_read_b128 v[214:217], v157 offset:53248
	ds_read_b128 v[218:221], v157 offset:54272
	ds_read_b128 v[222:225], v157 offset:55296
	ds_read_b128 v[226:229], v157 offset:56320
	global_load_lds_dwordx4 v[230:231], off
	v_lshl_add_u64 v[230:231], v[232:233], 0, s[36:37]
	s_add_i32 m0, s0, 0x2000
	s_add_i32 s0, s12, s17
	global_load_lds_dwordx4 v[230:231], off
	v_lshl_add_u64 v[230:231], v[234:235], 0, s[36:37]
	s_mov_b32 m0, s0
	s_nop 0
	global_load_lds_dwordx4 v[230:231], off
	v_lshl_add_u64 v[230:231], v[236:237], 0, s[36:37]
	s_add_i32 m0, s0, 0x2000
	s_nop 0
	global_load_lds_dwordx4 v[230:231], off
	v_lshl_add_u64 v[230:231], v[238:239], 0, s[36:37]
	s_mov_b32 m0, s10
	s_nop 0
	global_load_lds_dwordx4 v[230:231], off
	v_lshl_add_u64 v[230:231], v[240:241], 0, s[36:37]
	s_mov_b32 m0, s11
	s_nop 0
	global_load_lds_dwordx4 v[230:231], off
	s_waitcnt vmcnt(10)
	s_waitcnt lgkmcnt(0)
	s_barrier
	v_mfma_f32_16x16x32_bf16 v[52:55], v[128:131], v[178:181], v[52:55]
	v_mfma_f32_16x16x32_bf16 v[48:51], v[136:139], v[178:181], v[48:51]
	v_mfma_f32_16x16x32_bf16 v[36:39], v[128:131], v[206:209], v[36:39]
	v_mfma_f32_16x16x32_bf16 v[32:35], v[136:139], v[206:209], v[32:35]
	v_mfma_f32_16x16x32_bf16 v[20:23], v[128:131], v[214:217], v[20:23]
	v_mfma_f32_16x16x32_bf16 v[16:19], v[136:139], v[214:217], v[16:19]
	v_mfma_f32_16x16x32_bf16 v[4:7], v[128:131], v[222:225], v[4:7]
	v_mfma_f32_16x16x32_bf16 v[0:3], v[136:139], v[222:225], v[0:3]
	v_mfma_f32_16x16x32_bf16 v[52:55], v[132:135], v[202:205], v[52:55]
	v_mfma_f32_16x16x32_bf16 v[48:51], v[140:143], v[202:205], v[48:51]
	v_mfma_f32_16x16x32_bf16 v[36:39], v[132:135], v[210:213], v[36:39]
	v_mfma_f32_16x16x32_bf16 v[32:35], v[140:143], v[210:213], v[32:35]
	v_mfma_f32_16x16x32_bf16 v[20:23], v[132:135], v[218:221], v[20:23]
	v_mfma_f32_16x16x32_bf16 v[16:19], v[140:143], v[218:221], v[16:19]
	v_mfma_f32_16x16x32_bf16 v[4:7], v[132:135], v[226:229], v[4:7]
	v_mfma_f32_16x16x32_bf16 v[0:3], v[140:143], v[226:229], v[0:3]
	v_mfma_f32_16x16x32_bf16 v[60:63], v[144:147], v[178:181], v[60:63]
	v_mfma_f32_16x16x32_bf16 v[56:59], v[170:173], v[178:181], v[56:59]
	v_mfma_f32_16x16x32_bf16 v[44:47], v[144:147], v[206:209], v[44:47]
	v_mfma_f32_16x16x32_bf16 v[40:43], v[170:173], v[206:209], v[40:43]
	v_mfma_f32_16x16x32_bf16 v[28:31], v[144:147], v[214:217], v[28:31]
	v_mfma_f32_16x16x32_bf16 v[24:27], v[170:173], v[214:217], v[24:27]
	v_mfma_f32_16x16x32_bf16 v[12:15], v[144:147], v[222:225], v[12:15]
	v_mfma_f32_16x16x32_bf16 v[8:11], v[170:173], v[222:225], v[8:11]
	v_mfma_f32_16x16x32_bf16 v[60:63], v[148:151], v[202:205], v[60:63]
	v_mfma_f32_16x16x32_bf16 v[56:59], v[174:177], v[202:205], v[56:59]
	v_mfma_f32_16x16x32_bf16 v[44:47], v[148:151], v[210:213], v[44:47]
	v_mfma_f32_16x16x32_bf16 v[40:43], v[174:177], v[210:213], v[40:43]
	v_mfma_f32_16x16x32_bf16 v[28:31], v[148:151], v[218:221], v[28:31]
	v_mfma_f32_16x16x32_bf16 v[24:27], v[174:177], v[218:221], v[24:27]
	v_mfma_f32_16x16x32_bf16 v[12:15], v[148:151], v[226:229], v[12:15]
	v_mfma_f32_16x16x32_bf16 v[8:11], v[174:177], v[226:229], v[8:11]
	s_barrier
	s_add_u32 s42, s42, 0x100
	s_addc_u32 s43, s43, 0
	s_add_u32 s46, s46, 0x100
	s_addc_u32 s47, s47, 0
	s_cmp_ge_u32 s97, s31
	s_mov_b32 s0, s97
.LBB0_375:
	s_add_i32 s97, s0, 2
	s_add_u32 s2, s42, 0x80
	s_addc_u32 s1, s43, 0
	s_add_i32 s12, 0, 0x10000
	s_cmp_eq_u32 s13, s0
	s_cselect_b32 s1, s95, s1
	s_cselect_b32 s0, s94, s2
	s_cselect_b32 s15, s55, s47
	s_cselect_b32 s14, s54, s46
	s_add_i32 s2, 0, 0x14000
	v_add_u32_e32 v140, s12, v195
	v_add_u32_e32 v174, s2, v195
	ds_read_b128 v[128:131], v140
	ds_read_b128 v[132:135], v140 offset:1024
	ds_read_b128 v[136:139], v140 offset:2048
	ds_read_b128 v[140:143], v140 offset:3072
	ds_read_b128 v[144:147], v174
	ds_read_b128 v[148:151], v174 offset:1024
	ds_read_b128 v[170:173], v174 offset:2048
	ds_read_b128 v[174:177], v174 offset:3072
	v_lshl_add_u64 v[230:231], s[42:43], 0, v[166:167]
	s_add_i32 m0, s45, 0xc000
	ds_read_b128 v[178:181], v157
	ds_read_b128 v[202:205], v157 offset:1024
	ds_read_b128 v[206:209], v157 offset:2048
	ds_read_b128 v[210:213], v157 offset:3072
	ds_read_b128 v[214:217], v157 offset:4096
	ds_read_b128 v[218:221], v157 offset:5120
	ds_read_b128 v[222:225], v157 offset:6144
	ds_read_b128 v[226:229], v157 offset:7168
	global_load_lds_dwordx4 v[230:231], off
	v_lshl_add_u64 v[230:231], s[42:43], 0, v[168:169]
	s_add_i32 m0, s45, 0xe000
	s_nop 0
	global_load_lds_dwordx4 v[230:231], off
	s_waitcnt vmcnt(8)
	s_waitcnt lgkmcnt(0)
	s_barrier
	v_mfma_f32_16x16x32_bf16 v[120:123], v[128:131], v[178:181], v[120:123]
	v_mfma_f32_16x16x32_bf16 v[124:127], v[136:139], v[178:181], v[124:127]
	v_mfma_f32_16x16x32_bf16 v[100:103], v[128:131], v[206:209], v[100:103]
	v_mfma_f32_16x16x32_bf16 v[96:99], v[136:139], v[206:209], v[96:99]
	v_mfma_f32_16x16x32_bf16 v[84:87], v[128:131], v[214:217], v[84:87]
	v_mfma_f32_16x16x32_bf16 v[80:83], v[136:139], v[214:217], v[80:83]
	v_mfma_f32_16x16x32_bf16 v[68:71], v[128:131], v[222:225], v[68:71]
	v_mfma_f32_16x16x32_bf16 v[64:67], v[136:139], v[222:225], v[64:67]
	v_mfma_f32_16x16x32_bf16 v[120:123], v[132:135], v[202:205], v[120:123]
	v_mfma_f32_16x16x32_bf16 v[124:127], v[140:143], v[202:205], v[124:127]
	v_mfma_f32_16x16x32_bf16 v[100:103], v[132:135], v[210:213], v[100:103]
	v_mfma_f32_16x16x32_bf16 v[96:99], v[140:143], v[210:213], v[96:99]
	v_mfma_f32_16x16x32_bf16 v[84:87], v[132:135], v[218:221], v[84:87]
	v_mfma_f32_16x16x32_bf16 v[80:83], v[140:143], v[218:221], v[80:83]
	v_mfma_f32_16x16x32_bf16 v[68:71], v[132:135], v[226:229], v[68:71]
	v_mfma_f32_16x16x32_bf16 v[64:67], v[140:143], v[226:229], v[64:67]
	v_mfma_f32_16x16x32_bf16 v[116:119], v[144:147], v[178:181], v[116:119]
	v_mfma_f32_16x16x32_bf16 v[112:115], v[170:173], v[178:181], v[112:115]
	v_mfma_f32_16x16x32_bf16 v[108:111], v[144:147], v[206:209], v[108:111]
	v_mfma_f32_16x16x32_bf16 v[104:107], v[170:173], v[206:209], v[104:107]
	v_mfma_f32_16x16x32_bf16 v[92:95], v[144:147], v[214:217], v[92:95]
	v_mfma_f32_16x16x32_bf16 v[88:91], v[170:173], v[214:217], v[88:91]
	v_mfma_f32_16x16x32_bf16 v[76:79], v[144:147], v[222:225], v[76:79]
	v_mfma_f32_16x16x32_bf16 v[72:75], v[170:173], v[222:225], v[72:75]
	v_mfma_f32_16x16x32_bf16 v[116:119], v[148:151], v[202:205], v[116:119]
	v_mfma_f32_16x16x32_bf16 v[112:115], v[174:177], v[202:205], v[112:115]
	v_mfma_f32_16x16x32_bf16 v[108:111], v[148:151], v[210:213], v[108:111]
	v_mfma_f32_16x16x32_bf16 v[104:107], v[174:177], v[210:213], v[104:107]
	v_mfma_f32_16x16x32_bf16 v[92:95], v[148:151], v[218:221], v[92:95]
	v_mfma_f32_16x16x32_bf16 v[88:91], v[174:177], v[218:221], v[88:91]
	v_mfma_f32_16x16x32_bf16 v[76:79], v[148:151], v[226:229], v[76:79]
	v_mfma_f32_16x16x32_bf16 v[72:75], v[174:177], v[226:229], v[72:75]
	s_barrier
	s_add_i32 s12, s12, s17
	v_lshl_add_u64 v[230:231], s[14:15], 0, v[154:155]
	s_mov_b32 m0, s12
	ds_read_b128 v[178:181], v157 offset:16384
	ds_read_b128 v[202:205], v157 offset:17408
	ds_read_b128 v[206:209], v157 offset:18432
	ds_read_b128 v[210:213], v157 offset:19456
	ds_read_b128 v[214:217], v157 offset:20480
	ds_read_b128 v[218:221], v157 offset:21504
	ds_read_b128 v[222:225], v157 offset:22528
	ds_read_b128 v[226:229], v157 offset:23552
	global_load_lds_dwordx4 v[230:231], off
	s_add_i32 m0, s12, 0x2000
	v_lshl_add_u64 v[232:233], s[14:15], 0, v[162:163]
	s_add_u32 s14, s14, s24
	s_addc_u32 s15, s15, s25
	s_add_i32 s2, s2, s17
	global_load_lds_dwordx4 v[232:233], off
	v_lshl_add_u64 v[234:235], s[14:15], 0, v[154:155]
	s_mov_b32 m0, s2
	v_lshl_add_u64 v[236:237], s[14:15], 0, v[162:163]
	global_load_lds_dwordx4 v[234:235], off
	s_add_i32 m0, s2, 0x2000
	v_lshl_add_u64 v[238:239], s[0:1], 0, v[158:159]
	global_load_lds_dwordx4 v[236:237], off
	s_mov_b32 m0, s45
	v_lshl_add_u64 v[240:241], s[0:1], 0, v[160:161]
	global_load_lds_dwordx4 v[238:239], off
	s_mov_b32 m0, s83
	s_nop 0
	global_load_lds_dwordx4 v[240:241], off
	s_waitcnt vmcnt(8)
	s_waitcnt lgkmcnt(0)
	s_barrier
	v_mfma_f32_16x16x32_bf16 v[52:55], v[128:131], v[178:181], v[52:55]
	v_mfma_f32_16x16x32_bf16 v[48:51], v[136:139], v[178:181], v[48:51]
	v_mfma_f32_16x16x32_bf16 v[36:39], v[128:131], v[206:209], v[36:39]
	v_mfma_f32_16x16x32_bf16 v[32:35], v[136:139], v[206:209], v[32:35]
	v_mfma_f32_16x16x32_bf16 v[20:23], v[128:131], v[214:217], v[20:23]
	v_mfma_f32_16x16x32_bf16 v[16:19], v[136:139], v[214:217], v[16:19]
	v_mfma_f32_16x16x32_bf16 v[4:7], v[128:131], v[222:225], v[4:7]
	v_mfma_f32_16x16x32_bf16 v[0:3], v[136:139], v[222:225], v[0:3]
	v_mfma_f32_16x16x32_bf16 v[52:55], v[132:135], v[202:205], v[52:55]
	v_mfma_f32_16x16x32_bf16 v[48:51], v[140:143], v[202:205], v[48:51]
	v_mfma_f32_16x16x32_bf16 v[36:39], v[132:135], v[210:213], v[36:39]
	v_mfma_f32_16x16x32_bf16 v[32:35], v[140:143], v[210:213], v[32:35]
	v_mfma_f32_16x16x32_bf16 v[20:23], v[132:135], v[218:221], v[20:23]
	v_mfma_f32_16x16x32_bf16 v[16:19], v[140:143], v[218:221], v[16:19]
	v_mfma_f32_16x16x32_bf16 v[4:7], v[132:135], v[226:229], v[4:7]
	v_mfma_f32_16x16x32_bf16 v[0:3], v[140:143], v[226:229], v[0:3]
	v_mfma_f32_16x16x32_bf16 v[60:63], v[144:147], v[178:181], v[60:63]
	v_mfma_f32_16x16x32_bf16 v[56:59], v[170:173], v[178:181], v[56:59]
	v_mfma_f32_16x16x32_bf16 v[44:47], v[144:147], v[206:209], v[44:47]
	v_mfma_f32_16x16x32_bf16 v[40:43], v[170:173], v[206:209], v[40:43]
	v_mfma_f32_16x16x32_bf16 v[28:31], v[144:147], v[214:217], v[28:31]
	v_mfma_f32_16x16x32_bf16 v[24:27], v[170:173], v[214:217], v[24:27]
	v_mfma_f32_16x16x32_bf16 v[12:15], v[144:147], v[222:225], v[12:15]
	v_mfma_f32_16x16x32_bf16 v[8:11], v[170:173], v[222:225], v[8:11]
	v_mfma_f32_16x16x32_bf16 v[60:63], v[148:151], v[202:205], v[60:63]
	v_mfma_f32_16x16x32_bf16 v[56:59], v[174:177], v[202:205], v[56:59]
	v_mfma_f32_16x16x32_bf16 v[44:47], v[148:151], v[210:213], v[44:47]
	v_mfma_f32_16x16x32_bf16 v[40:43], v[174:177], v[210:213], v[40:43]
	v_mfma_f32_16x16x32_bf16 v[28:31], v[148:151], v[218:221], v[28:31]
	v_mfma_f32_16x16x32_bf16 v[24:27], v[174:177], v[218:221], v[24:27]
	v_mfma_f32_16x16x32_bf16 v[12:15], v[148:151], v[226:229], v[12:15]
	v_mfma_f32_16x16x32_bf16 v[8:11], v[174:177], v[226:229], v[8:11]
	s_barrier
	s_add_i32 s2, 0, 0x18000
	s_add_i32 s12, 0, 0x1c000
	v_add_u32_e32 v140, s2, v195
	v_add_u32_e32 v174, s12, v195
	ds_read_b128 v[128:131], v140
	ds_read_b128 v[132:135], v140 offset:1024
	ds_read_b128 v[136:139], v140 offset:2048
	ds_read_b128 v[140:143], v140 offset:3072
	ds_read_b128 v[144:147], v174
	ds_read_b128 v[148:151], v174 offset:1024
	ds_read_b128 v[170:173], v174 offset:2048
	ds_read_b128 v[174:177], v174 offset:3072
	s_add_u32 s0, s0, s8
	s_addc_u32 s1, s1, s9
	s_mov_b32 m0, s28
	v_lshl_add_u64 v[242:243], s[0:1], 0, v[158:159]
	ds_read_b128 v[178:181], v157 offset:32768
	ds_read_b128 v[202:205], v157 offset:33792
	ds_read_b128 v[206:209], v157 offset:34816
	ds_read_b128 v[210:213], v157 offset:35840
	ds_read_b128 v[214:217], v157 offset:36864
	ds_read_b128 v[218:221], v157 offset:37888
	ds_read_b128 v[222:225], v157 offset:38912
	ds_read_b128 v[226:229], v157 offset:39936
	global_load_lds_dwordx4 v[242:243], off
	v_lshl_add_u64 v[242:243], s[0:1], 0, v[160:161]
	s_mov_b32 m0, s29
	s_nop 0
	global_load_lds_dwordx4 v[242:243], off
	s_waitcnt vmcnt(8)
	s_waitcnt lgkmcnt(0)
	s_barrier
	v_mfma_f32_16x16x32_bf16 v[120:123], v[128:131], v[178:181], v[120:123]
	v_mfma_f32_16x16x32_bf16 v[124:127], v[136:139], v[178:181], v[124:127]
	v_mfma_f32_16x16x32_bf16 v[100:103], v[128:131], v[206:209], v[100:103]
	v_mfma_f32_16x16x32_bf16 v[96:99], v[136:139], v[206:209], v[96:99]
	v_mfma_f32_16x16x32_bf16 v[84:87], v[128:131], v[214:217], v[84:87]
	v_mfma_f32_16x16x32_bf16 v[80:83], v[136:139], v[214:217], v[80:83]
	v_mfma_f32_16x16x32_bf16 v[68:71], v[128:131], v[222:225], v[68:71]
	v_mfma_f32_16x16x32_bf16 v[64:67], v[136:139], v[222:225], v[64:67]
	v_mfma_f32_16x16x32_bf16 v[120:123], v[132:135], v[202:205], v[120:123]
	v_mfma_f32_16x16x32_bf16 v[124:127], v[140:143], v[202:205], v[124:127]
	v_mfma_f32_16x16x32_bf16 v[100:103], v[132:135], v[210:213], v[100:103]
	v_mfma_f32_16x16x32_bf16 v[96:99], v[140:143], v[210:213], v[96:99]
	v_mfma_f32_16x16x32_bf16 v[84:87], v[132:135], v[218:221], v[84:87]
	v_mfma_f32_16x16x32_bf16 v[80:83], v[140:143], v[218:221], v[80:83]
	v_mfma_f32_16x16x32_bf16 v[68:71], v[132:135], v[226:229], v[68:71]
	v_mfma_f32_16x16x32_bf16 v[64:67], v[140:143], v[226:229], v[64:67]
	v_mfma_f32_16x16x32_bf16 v[116:119], v[144:147], v[178:181], v[116:119]
	v_mfma_f32_16x16x32_bf16 v[112:115], v[170:173], v[178:181], v[112:115]
	v_mfma_f32_16x16x32_bf16 v[108:111], v[144:147], v[206:209], v[108:111]
	v_mfma_f32_16x16x32_bf16 v[104:107], v[170:173], v[206:209], v[104:107]
	v_mfma_f32_16x16x32_bf16 v[92:95], v[144:147], v[214:217], v[92:95]
	v_mfma_f32_16x16x32_bf16 v[88:91], v[170:173], v[214:217], v[88:91]
	v_mfma_f32_16x16x32_bf16 v[76:79], v[144:147], v[222:225], v[76:79]
	v_mfma_f32_16x16x32_bf16 v[72:75], v[170:173], v[222:225], v[72:75]
	v_mfma_f32_16x16x32_bf16 v[116:119], v[148:151], v[202:205], v[116:119]
	v_mfma_f32_16x16x32_bf16 v[112:115], v[174:177], v[202:205], v[112:115]
	v_mfma_f32_16x16x32_bf16 v[108:111], v[148:151], v[210:213], v[108:111]
	v_mfma_f32_16x16x32_bf16 v[104:107], v[174:177], v[210:213], v[104:107]
	v_mfma_f32_16x16x32_bf16 v[92:95], v[148:151], v[218:221], v[92:95]
	v_mfma_f32_16x16x32_bf16 v[88:91], v[174:177], v[218:221], v[88:91]
	v_mfma_f32_16x16x32_bf16 v[76:79], v[148:151], v[226:229], v[76:79]
	v_mfma_f32_16x16x32_bf16 v[72:75], v[174:177], v[226:229], v[72:75]
	s_barrier
	s_add_i32 s0, s2, s17
	v_lshl_add_u64 v[230:231], v[230:231], 0, s[36:37]
	s_mov_b32 m0, s0
	ds_read_b128 v[178:181], v157 offset:49152
	ds_read_b128 v[202:205], v157 offset:50176
	ds_read_b128 v[206:209], v157 offset:51200
	ds_read_b128 v[210:213], v157 offset:52224
	ds_read_b128 v[214:217], v157 offset:53248
	ds_read_b128 v[218:221], v157 offset:54272
	ds_read_b128 v[222:225], v157 offset:55296
	ds_read_b128 v[226:229], v157 offset:56320
	global_load_lds_dwordx4 v[230:231], off
	v_lshl_add_u64 v[230:231], v[232:233], 0, s[36:37]
	s_add_i32 m0, s0, 0x2000
	s_add_i32 s0, s12, s17
	global_load_lds_dwordx4 v[230:231], off
	v_lshl_add_u64 v[230:231], v[234:235], 0, s[36:37]
	s_mov_b32 m0, s0
	s_nop 0
	global_load_lds_dwordx4 v[230:231], off
	v_lshl_add_u64 v[230:231], v[236:237], 0, s[36:37]
	s_add_i32 m0, s0, 0x2000
	s_nop 0
	global_load_lds_dwordx4 v[230:231], off
	v_lshl_add_u64 v[230:231], v[238:239], 0, s[36:37]
	s_mov_b32 m0, s10
	s_nop 0
	global_load_lds_dwordx4 v[230:231], off
	v_lshl_add_u64 v[230:231], v[240:241], 0, s[36:37]
	s_mov_b32 m0, s11
	s_nop 0
	global_load_lds_dwordx4 v[230:231], off
	s_waitcnt vmcnt(8)
	s_waitcnt lgkmcnt(0)
	s_barrier
	v_mfma_f32_16x16x32_bf16 v[52:55], v[128:131], v[178:181], v[52:55]
	v_mfma_f32_16x16x32_bf16 v[48:51], v[136:139], v[178:181], v[48:51]
	v_mfma_f32_16x16x32_bf16 v[36:39], v[128:131], v[206:209], v[36:39]
	v_mfma_f32_16x16x32_bf16 v[32:35], v[136:139], v[206:209], v[32:35]
	v_mfma_f32_16x16x32_bf16 v[20:23], v[128:131], v[214:217], v[20:23]
	v_mfma_f32_16x16x32_bf16 v[16:19], v[136:139], v[214:217], v[16:19]
	v_mfma_f32_16x16x32_bf16 v[4:7], v[128:131], v[222:225], v[4:7]
	v_mfma_f32_16x16x32_bf16 v[0:3], v[136:139], v[222:225], v[0:3]
	v_mfma_f32_16x16x32_bf16 v[52:55], v[132:135], v[202:205], v[52:55]
	v_mfma_f32_16x16x32_bf16 v[48:51], v[140:143], v[202:205], v[48:51]
	v_mfma_f32_16x16x32_bf16 v[36:39], v[132:135], v[210:213], v[36:39]
	v_mfma_f32_16x16x32_bf16 v[32:35], v[140:143], v[210:213], v[32:35]
	v_mfma_f32_16x16x32_bf16 v[20:23], v[132:135], v[218:221], v[20:23]
	v_mfma_f32_16x16x32_bf16 v[16:19], v[140:143], v[218:221], v[16:19]
	v_mfma_f32_16x16x32_bf16 v[4:7], v[132:135], v[226:229], v[4:7]
	v_mfma_f32_16x16x32_bf16 v[0:3], v[140:143], v[226:229], v[0:3]
	v_mfma_f32_16x16x32_bf16 v[60:63], v[144:147], v[178:181], v[60:63]
	v_mfma_f32_16x16x32_bf16 v[56:59], v[170:173], v[178:181], v[56:59]
	v_mfma_f32_16x16x32_bf16 v[44:47], v[144:147], v[206:209], v[44:47]
	v_mfma_f32_16x16x32_bf16 v[40:43], v[170:173], v[206:209], v[40:43]
	v_mfma_f32_16x16x32_bf16 v[28:31], v[144:147], v[214:217], v[28:31]
	v_mfma_f32_16x16x32_bf16 v[24:27], v[170:173], v[214:217], v[24:27]
	v_mfma_f32_16x16x32_bf16 v[12:15], v[144:147], v[222:225], v[12:15]
	v_mfma_f32_16x16x32_bf16 v[8:11], v[170:173], v[222:225], v[8:11]
	v_mfma_f32_16x16x32_bf16 v[60:63], v[148:151], v[202:205], v[60:63]
	v_mfma_f32_16x16x32_bf16 v[56:59], v[174:177], v[202:205], v[56:59]
	v_mfma_f32_16x16x32_bf16 v[44:47], v[148:151], v[210:213], v[44:47]
	v_mfma_f32_16x16x32_bf16 v[40:43], v[174:177], v[210:213], v[40:43]
	v_mfma_f32_16x16x32_bf16 v[28:31], v[148:151], v[218:221], v[28:31]
	v_mfma_f32_16x16x32_bf16 v[24:27], v[174:177], v[218:221], v[24:27]
	v_mfma_f32_16x16x32_bf16 v[12:15], v[148:151], v[226:229], v[12:15]
	v_mfma_f32_16x16x32_bf16 v[8:11], v[174:177], v[226:229], v[8:11]
	s_barrier
	s_add_u32 s42, s42, 0x100
	s_addc_u32 s43, s43, 0
	s_add_u32 s46, s46, 0x100
	s_addc_u32 s47, s47, 0
	s_cmp_ge_u32 s97, s31
	s_mov_b32 s0, s97
	s_cbranch_scc0 .LBB0_375
	s_and_b64 vcc, exec, s[74:75]
	s_cbranch_vccz .LBB0_378
	s_barrier

.Lpeel_join482_1:
	s_waitcnt lgkmcnt(0)
	s_barrier
	v_mfma_f32_16x16x32_bf16 v[124:127], v[128:131], v[202:205], 0
	v_mfma_f32_16x16x32_bf16 v[120:123], v[146:149], v[202:205], 0
	v_mfma_f32_16x16x32_bf16 v[108:111], v[128:131], v[210:213], 0
	v_mfma_f32_16x16x32_bf16 v[104:107], v[146:149], v[210:213], 0
	v_mfma_f32_16x16x32_bf16 v[92:95], v[128:131], v[218:221], 0
	v_mfma_f32_16x16x32_bf16 v[88:91], v[146:149], v[218:221], 0
	v_mfma_f32_16x16x32_bf16 v[76:79], v[128:131], v[226:229], 0
	v_mfma_f32_16x16x32_bf16 v[72:75], v[146:149], v[226:229], 0
	v_mfma_f32_16x16x32_bf16 v[124:127], v[132:135], v[206:209], v[124:127]
	v_mfma_f32_16x16x32_bf16 v[120:123], v[158:161], v[206:209], v[120:123]
	v_mfma_f32_16x16x32_bf16 v[108:111], v[132:135], v[214:217], v[108:111]
	v_mfma_f32_16x16x32_bf16 v[104:107], v[158:161], v[214:217], v[104:107]
	v_mfma_f32_16x16x32_bf16 v[92:95], v[132:135], v[222:225], v[92:95]
	v_mfma_f32_16x16x32_bf16 v[88:91], v[158:161], v[222:225], v[88:91]
	v_mfma_f32_16x16x32_bf16 v[76:79], v[132:135], v[230:233], v[76:79]
	v_mfma_f32_16x16x32_bf16 v[72:75], v[158:161], v[230:233], v[72:75]
	v_mfma_f32_16x16x32_bf16 v[116:119], v[168:171], v[202:205], 0
	v_mfma_f32_16x16x32_bf16 v[112:115], v[176:179], v[202:205], 0
	v_mfma_f32_16x16x32_bf16 v[100:103], v[168:171], v[210:213], 0
	v_mfma_f32_16x16x32_bf16 v[96:99], v[176:179], v[210:213], 0
	v_mfma_f32_16x16x32_bf16 v[84:87], v[168:171], v[218:221], 0
	v_mfma_f32_16x16x32_bf16 v[80:83], v[176:179], v[218:221], 0
	v_mfma_f32_16x16x32_bf16 v[68:71], v[168:171], v[226:229], 0
	v_mfma_f32_16x16x32_bf16 v[64:67], v[176:179], v[226:229], 0
	v_mfma_f32_16x16x32_bf16 v[116:119], v[172:175], v[206:209], v[116:119]
	v_mfma_f32_16x16x32_bf16 v[112:115], v[194:197], v[206:209], v[112:115]
	v_mfma_f32_16x16x32_bf16 v[100:103], v[172:175], v[214:217], v[100:103]
	v_mfma_f32_16x16x32_bf16 v[96:99], v[194:197], v[214:217], v[96:99]
	v_mfma_f32_16x16x32_bf16 v[84:87], v[172:175], v[222:225], v[84:87]
	v_mfma_f32_16x16x32_bf16 v[80:83], v[194:197], v[222:225], v[80:83]
	v_mfma_f32_16x16x32_bf16 v[68:71], v[172:175], v[230:233], v[68:71]
	v_mfma_f32_16x16x32_bf16 v[64:67], v[194:197], v[230:233], v[64:67]
	s_barrier
	s_add_i32 s15, s15, s2
	v_lshl_add_u64 v[150:151], s[82:83], 0, v[154:155]
	s_mov_b32 m0, s15
	ds_read_b128 v[202:205], v167 offset:16384
	ds_read_b128 v[206:209], v167 offset:17408
	ds_read_b128 v[210:213], v167 offset:18432
	ds_read_b128 v[214:217], v167 offset:19456
	ds_read_b128 v[218:221], v167 offset:20480
	ds_read_b128 v[222:225], v167 offset:21504
	ds_read_b128 v[226:229], v167 offset:22528
	ds_read_b128 v[230:233], v167 offset:23552
	global_load_lds_dwordx4 v[150:151], off
	s_add_i32 m0, s15, 0x2000
	v_lshl_add_u64 v[162:163], s[82:83], 0, v[140:141]
	s_add_u32 s82, s82, s24
	s_addc_u32 s83, s83, s25
	s_add_i32 s14, s14, s2
	global_load_lds_dwordx4 v[162:163], off
	v_lshl_add_u64 v[180:181], s[82:83], 0, v[154:155]
	s_mov_b32 m0, s14
	v_lshl_add_u64 v[234:235], s[82:83], 0, v[140:141]
	global_load_lds_dwordx4 v[180:181], off
	s_add_i32 m0, s14, 0x2000
	v_lshl_add_u64 v[236:237], s[0:1], 0, v[136:137]
	global_load_lds_dwordx4 v[234:235], off
	s_mov_b32 m0, s3
	v_lshl_add_u64 v[238:239], s[0:1], 0, v[138:139]
	global_load_lds_dwordx4 v[236:237], off
	s_mov_b32 m0, s10
	s_nop 0
	global_load_lds_dwordx4 v[238:239], off
	s_cmp_eq_u32 s92, 1
	s_cbranch_scc1 .Lpeel_strict482_2
	s_waitcnt vmcnt(24)
	s_branch .Lpeel_join482_2

.Lpeel_join482_2:
	s_waitcnt lgkmcnt(0)
	s_barrier
	v_mfma_f32_16x16x32_bf16 v[60:63], v[128:131], v[202:205], 0
	v_mfma_f32_16x16x32_bf16 v[56:59], v[146:149], v[202:205], 0
	v_mfma_f32_16x16x32_bf16 v[44:47], v[128:131], v[210:213], 0
	v_mfma_f32_16x16x32_bf16 v[40:43], v[146:149], v[210:213], 0
	v_mfma_f32_16x16x32_bf16 v[28:31], v[128:131], v[218:221], 0
	v_mfma_f32_16x16x32_bf16 v[24:27], v[146:149], v[218:221], 0
	v_mfma_f32_16x16x32_bf16 v[12:15], v[128:131], v[226:229], 0
	v_mfma_f32_16x16x32_bf16 v[8:11], v[146:149], v[226:229], 0
	v_mfma_f32_16x16x32_bf16 v[60:63], v[132:135], v[206:209], v[60:63]
	v_mfma_f32_16x16x32_bf16 v[56:59], v[158:161], v[206:209], v[56:59]
	v_mfma_f32_16x16x32_bf16 v[44:47], v[132:135], v[214:217], v[44:47]
	v_mfma_f32_16x16x32_bf16 v[40:43], v[158:161], v[214:217], v[40:43]
	v_mfma_f32_16x16x32_bf16 v[28:31], v[132:135], v[222:225], v[28:31]
	v_mfma_f32_16x16x32_bf16 v[24:27], v[158:161], v[222:225], v[24:27]
	v_mfma_f32_16x16x32_bf16 v[12:15], v[132:135], v[230:233], v[12:15]
	v_mfma_f32_16x16x32_bf16 v[8:11], v[158:161], v[230:233], v[8:11]
	v_mfma_f32_16x16x32_bf16 v[52:55], v[168:171], v[202:205], 0
	v_mfma_f32_16x16x32_bf16 v[48:51], v[176:179], v[202:205], 0
	v_mfma_f32_16x16x32_bf16 v[36:39], v[168:171], v[210:213], 0
	v_mfma_f32_16x16x32_bf16 v[32:35], v[176:179], v[210:213], 0
	v_mfma_f32_16x16x32_bf16 v[20:23], v[168:171], v[218:221], 0
	v_mfma_f32_16x16x32_bf16 v[16:19], v[176:179], v[218:221], 0
	v_mfma_f32_16x16x32_bf16 v[4:7], v[168:171], v[226:229], 0
	v_mfma_f32_16x16x32_bf16 v[0:3], v[176:179], v[226:229], 0
	v_mfma_f32_16x16x32_bf16 v[52:55], v[172:175], v[206:209], v[52:55]
	v_mfma_f32_16x16x32_bf16 v[48:51], v[194:197], v[206:209], v[48:51]
	v_mfma_f32_16x16x32_bf16 v[36:39], v[172:175], v[214:217], v[36:39]
	v_mfma_f32_16x16x32_bf16 v[32:35], v[194:197], v[214:217], v[32:35]
	v_mfma_f32_16x16x32_bf16 v[20:23], v[172:175], v[222:225], v[20:23]
	v_mfma_f32_16x16x32_bf16 v[16:19], v[194:197], v[222:225], v[16:19]
	v_mfma_f32_16x16x32_bf16 v[4:7], v[172:175], v[230:233], v[4:7]
	v_mfma_f32_16x16x32_bf16 v[0:3], v[194:197], v[230:233], v[0:3]
	s_barrier
	s_add_i32 s14, 0, 0x18000
	s_add_i32 s15, 0, 0x1c000
	v_add_u32_e32 v158, s14, v165
	v_add_u32_e32 v193, s15, v165
	ds_read_b128 v[128:131], v158
	ds_read_b128 v[132:135], v158 offset:1024
	ds_read_b128 v[146:149], v158 offset:2048
	ds_read_b128 v[158:161], v158 offset:3072
	ds_read_b128 v[168:171], v193
	ds_read_b128 v[172:175], v193 offset:1024
	ds_read_b128 v[176:179], v193 offset:2048
	ds_read_b128 v[194:197], v193 offset:3072
	s_add_u32 s0, s0, s8
	s_addc_u32 s1, s1, s9
	s_mov_b32 m0, s11
	v_lshl_add_u64 v[240:241], s[0:1], 0, v[136:137]
	ds_read_b128 v[202:205], v167 offset:32768
	ds_read_b128 v[206:209], v167 offset:33792
	ds_read_b128 v[210:213], v167 offset:34816
	ds_read_b128 v[214:217], v167 offset:35840
	ds_read_b128 v[218:221], v167 offset:36864
	ds_read_b128 v[222:225], v167 offset:37888
	ds_read_b128 v[226:229], v167 offset:38912
	ds_read_b128 v[230:233], v167 offset:39936
	global_load_lds_dwordx4 v[240:241], off
	v_lshl_add_u64 v[240:241], s[0:1], 0, v[138:139]
	s_mov_b32 m0, s13
	s_nop 0
	global_load_lds_dwordx4 v[240:241], off
	s_waitcnt vmcnt(8)
	s_waitcnt lgkmcnt(0)
	s_barrier
	v_mfma_f32_16x16x32_bf16 v[124:127], v[128:131], v[202:205], v[124:127]
	v_mfma_f32_16x16x32_bf16 v[120:123], v[146:149], v[202:205], v[120:123]
	v_mfma_f32_16x16x32_bf16 v[108:111], v[128:131], v[210:213], v[108:111]
	v_mfma_f32_16x16x32_bf16 v[104:107], v[146:149], v[210:213], v[104:107]
	v_mfma_f32_16x16x32_bf16 v[92:95], v[128:131], v[218:221], v[92:95]
	v_mfma_f32_16x16x32_bf16 v[88:91], v[146:149], v[218:221], v[88:91]
	v_mfma_f32_16x16x32_bf16 v[76:79], v[128:131], v[226:229], v[76:79]
	v_mfma_f32_16x16x32_bf16 v[72:75], v[146:149], v[226:229], v[72:75]
	v_mfma_f32_16x16x32_bf16 v[124:127], v[132:135], v[206:209], v[124:127]
	v_mfma_f32_16x16x32_bf16 v[120:123], v[158:161], v[206:209], v[120:123]
	v_mfma_f32_16x16x32_bf16 v[108:111], v[132:135], v[214:217], v[108:111]
	v_mfma_f32_16x16x32_bf16 v[104:107], v[158:161], v[214:217], v[104:107]
	v_mfma_f32_16x16x32_bf16 v[92:95], v[132:135], v[222:225], v[92:95]
	v_mfma_f32_16x16x32_bf16 v[88:91], v[158:161], v[222:225], v[88:91]
	v_mfma_f32_16x16x32_bf16 v[76:79], v[132:135], v[230:233], v[76:79]
	v_mfma_f32_16x16x32_bf16 v[72:75], v[158:161], v[230:233], v[72:75]
	v_mfma_f32_16x16x32_bf16 v[116:119], v[168:171], v[202:205], v[116:119]
	v_mfma_f32_16x16x32_bf16 v[112:115], v[176:179], v[202:205], v[112:115]
	v_mfma_f32_16x16x32_bf16 v[100:103], v[168:171], v[210:213], v[100:103]
	v_mfma_f32_16x16x32_bf16 v[96:99], v[176:179], v[210:213], v[96:99]
	v_mfma_f32_16x16x32_bf16 v[84:87], v[168:171], v[218:221], v[84:87]
	v_mfma_f32_16x16x32_bf16 v[80:83], v[176:179], v[218:221], v[80:83]
	v_mfma_f32_16x16x32_bf16 v[68:71], v[168:171], v[226:229], v[68:71]
	v_mfma_f32_16x16x32_bf16 v[64:67], v[176:179], v[226:229], v[64:67]
	v_mfma_f32_16x16x32_bf16 v[116:119], v[172:175], v[206:209], v[116:119]
	v_mfma_f32_16x16x32_bf16 v[112:115], v[194:197], v[206:209], v[112:115]
	v_mfma_f32_16x16x32_bf16 v[100:103], v[172:175], v[214:217], v[100:103]
	v_mfma_f32_16x16x32_bf16 v[96:99], v[194:197], v[214:217], v[96:99]
	v_mfma_f32_16x16x32_bf16 v[84:87], v[172:175], v[222:225], v[84:87]
	v_mfma_f32_16x16x32_bf16 v[80:83], v[194:197], v[222:225], v[80:83]
	v_mfma_f32_16x16x32_bf16 v[68:71], v[172:175], v[230:233], v[68:71]
	v_mfma_f32_16x16x32_bf16 v[64:67], v[194:197], v[230:233], v[64:67]
	s_barrier
	s_add_i32 s0, s14, s2
	v_lshl_add_u64 v[150:151], v[150:151], 0, s[36:37]
	s_mov_b32 m0, s0
	ds_read_b128 v[202:205], v167 offset:49152
	ds_read_b128 v[206:209], v167 offset:50176
	ds_read_b128 v[210:213], v167 offset:51200
	ds_read_b128 v[214:217], v167 offset:52224
	ds_read_b128 v[218:221], v167 offset:53248
	ds_read_b128 v[222:225], v167 offset:54272
	ds_read_b128 v[226:229], v167 offset:55296
	ds_read_b128 v[230:233], v167 offset:56320
	global_load_lds_dwordx4 v[150:151], off
	v_lshl_add_u64 v[150:151], v[162:163], 0, s[36:37]
	s_add_i32 m0, s0, 0x2000
	s_add_i32 s0, s15, s2
	global_load_lds_dwordx4 v[150:151], off
	v_lshl_add_u64 v[150:151], v[180:181], 0, s[36:37]
	s_mov_b32 m0, s0
	s_nop 0
	global_load_lds_dwordx4 v[150:151], off
	v_lshl_add_u64 v[150:151], v[234:235], 0, s[36:37]
	s_add_i32 m0, s0, 0x2000
	s_nop 0
	global_load_lds_dwordx4 v[150:151], off
	v_lshl_add_u64 v[150:151], v[236:237], 0, s[36:37]
	s_mov_b32 m0, s18
	s_nop 0
	global_load_lds_dwordx4 v[150:151], off
	v_lshl_add_u64 v[150:151], v[238:239], 0, s[36:37]
	s_mov_b32 m0, s28
	s_nop 0
	global_load_lds_dwordx4 v[150:151], off
	s_waitcnt vmcnt(8)
	s_waitcnt lgkmcnt(0)
	s_barrier
	v_mfma_f32_16x16x32_bf16 v[60:63], v[128:131], v[202:205], v[60:63]
	v_mfma_f32_16x16x32_bf16 v[56:59], v[146:149], v[202:205], v[56:59]
	v_mfma_f32_16x16x32_bf16 v[44:47], v[128:131], v[210:213], v[44:47]
	v_mfma_f32_16x16x32_bf16 v[40:43], v[146:149], v[210:213], v[40:43]
	v_mfma_f32_16x16x32_bf16 v[28:31], v[128:131], v[218:221], v[28:31]
	v_mfma_f32_16x16x32_bf16 v[24:27], v[146:149], v[218:221], v[24:27]
	v_mfma_f32_16x16x32_bf16 v[12:15], v[128:131], v[226:229], v[12:15]
	v_mfma_f32_16x16x32_bf16 v[8:11], v[146:149], v[226:229], v[8:11]
	v_mfma_f32_16x16x32_bf16 v[60:63], v[132:135], v[206:209], v[60:63]
	v_mfma_f32_16x16x32_bf16 v[56:59], v[158:161], v[206:209], v[56:59]
	v_mfma_f32_16x16x32_bf16 v[44:47], v[132:135], v[214:217], v[44:47]
	v_mfma_f32_16x16x32_bf16 v[40:43], v[158:161], v[214:217], v[40:43]
	v_mfma_f32_16x16x32_bf16 v[28:31], v[132:135], v[222:225], v[28:31]
	v_mfma_f32_16x16x32_bf16 v[24:27], v[158:161], v[222:225], v[24:27]
	v_mfma_f32_16x16x32_bf16 v[12:15], v[132:135], v[230:233], v[12:15]
	v_mfma_f32_16x16x32_bf16 v[8:11], v[158:161], v[230:233], v[8:11]
	v_mfma_f32_16x16x32_bf16 v[52:55], v[168:171], v[202:205], v[52:55]
	v_mfma_f32_16x16x32_bf16 v[48:51], v[176:179], v[202:205], v[48:51]
	v_mfma_f32_16x16x32_bf16 v[36:39], v[168:171], v[210:213], v[36:39]
	v_mfma_f32_16x16x32_bf16 v[32:35], v[176:179], v[210:213], v[32:35]
	v_mfma_f32_16x16x32_bf16 v[20:23], v[168:171], v[218:221], v[20:23]
	v_mfma_f32_16x16x32_bf16 v[16:19], v[176:179], v[218:221], v[16:19]
	v_mfma_f32_16x16x32_bf16 v[4:7], v[168:171], v[226:229], v[4:7]
	v_mfma_f32_16x16x32_bf16 v[0:3], v[176:179], v[226:229], v[0:3]
	v_mfma_f32_16x16x32_bf16 v[52:55], v[172:175], v[206:209], v[52:55]
	v_mfma_f32_16x16x32_bf16 v[48:51], v[194:197], v[206:209], v[48:51]
	v_mfma_f32_16x16x32_bf16 v[36:39], v[172:175], v[214:217], v[36:39]
	v_mfma_f32_16x16x32_bf16 v[32:35], v[194:197], v[214:217], v[32:35]
	v_mfma_f32_16x16x32_bf16 v[20:23], v[172:175], v[222:225], v[20:23]
	v_mfma_f32_16x16x32_bf16 v[16:19], v[194:197], v[222:225], v[16:19]
	v_mfma_f32_16x16x32_bf16 v[4:7], v[172:175], v[230:233], v[4:7]
	v_mfma_f32_16x16x32_bf16 v[0:3], v[194:197], v[230:233], v[0:3]
	s_barrier
	s_add_u32 s42, s42, 0x100
	s_addc_u32 s43, s43, 0
	s_add_u32 s44, s44, 0x100
	s_addc_u32 s45, s45, 0
	s_cmp_ge_u32 s47, s31
	s_mov_b32 s0, s47
.LBB0_482:
	s_add_i32 s47, s0, 2
	s_add_u32 s14, s42, 0x80
	s_addc_u32 s1, s43, 0
	s_add_i32 s15, 0, 0x10000
	s_cmp_eq_u32 s29, s0
	s_cselect_b32 s1, s77, s1
	s_cselect_b32 s0, s76, s14
	v_add_u32_e32 v150, s15, v165
	s_cselect_b32 s83, s79, s45
	s_cselect_b32 s82, s78, s44
	s_add_i32 s14, 0, 0x14000
	ds_read_b128 v[128:131], v150
	ds_read_b128 v[132:135], v150 offset:1024
	ds_read_b128 v[146:149], v150 offset:2048
	ds_read_b128 v[158:161], v150 offset:3072
	v_add_u32_e32 v150, s14, v165
	ds_read_b128 v[168:171], v150
	ds_read_b128 v[172:175], v150 offset:1024
	ds_read_b128 v[176:179], v150 offset:2048
	ds_read_b128 v[194:197], v150 offset:3072
	v_lshl_add_u64 v[150:151], s[42:43], 0, v[142:143]
	s_add_i32 m0, s3, 0xc000
	ds_read_b128 v[202:205], v167
	ds_read_b128 v[206:209], v167 offset:1024
	ds_read_b128 v[210:213], v167 offset:2048
	ds_read_b128 v[214:217], v167 offset:3072
	ds_read_b128 v[218:221], v167 offset:4096
	ds_read_b128 v[222:225], v167 offset:5120
	ds_read_b128 v[226:229], v167 offset:6144
	ds_read_b128 v[230:233], v167 offset:7168
	global_load_lds_dwordx4 v[150:151], off
	v_lshl_add_u64 v[150:151], s[42:43], 0, v[144:145]
	s_add_i32 m0, s3, 0xe000
	s_nop 0
	global_load_lds_dwordx4 v[150:151], off
	s_waitcnt vmcnt(8)
	s_waitcnt lgkmcnt(0)
	s_barrier
	v_mfma_f32_16x16x32_bf16 v[124:127], v[128:131], v[202:205], v[124:127]
	v_mfma_f32_16x16x32_bf16 v[120:123], v[146:149], v[202:205], v[120:123]
	v_mfma_f32_16x16x32_bf16 v[108:111], v[128:131], v[210:213], v[108:111]
	v_mfma_f32_16x16x32_bf16 v[104:107], v[146:149], v[210:213], v[104:107]
	v_mfma_f32_16x16x32_bf16 v[92:95], v[128:131], v[218:221], v[92:95]
	v_mfma_f32_16x16x32_bf16 v[88:91], v[146:149], v[218:221], v[88:91]
	v_mfma_f32_16x16x32_bf16 v[76:79], v[128:131], v[226:229], v[76:79]
	v_mfma_f32_16x16x32_bf16 v[72:75], v[146:149], v[226:229], v[72:75]
	v_mfma_f32_16x16x32_bf16 v[124:127], v[132:135], v[206:209], v[124:127]
	v_mfma_f32_16x16x32_bf16 v[120:123], v[158:161], v[206:209], v[120:123]
	v_mfma_f32_16x16x32_bf16 v[108:111], v[132:135], v[214:217], v[108:111]
	v_mfma_f32_16x16x32_bf16 v[104:107], v[158:161], v[214:217], v[104:107]
	v_mfma_f32_16x16x32_bf16 v[92:95], v[132:135], v[222:225], v[92:95]
	v_mfma_f32_16x16x32_bf16 v[88:91], v[158:161], v[222:225], v[88:91]
	v_mfma_f32_16x16x32_bf16 v[76:79], v[132:135], v[230:233], v[76:79]
	v_mfma_f32_16x16x32_bf16 v[72:75], v[158:161], v[230:233], v[72:75]
	v_mfma_f32_16x16x32_bf16 v[116:119], v[168:171], v[202:205], v[116:119]
	v_mfma_f32_16x16x32_bf16 v[112:115], v[176:179], v[202:205], v[112:115]
	v_mfma_f32_16x16x32_bf16 v[100:103], v[168:171], v[210:213], v[100:103]
	v_mfma_f32_16x16x32_bf16 v[96:99], v[176:179], v[210:213], v[96:99]
	v_mfma_f32_16x16x32_bf16 v[84:87], v[168:171], v[218:221], v[84:87]
	v_mfma_f32_16x16x32_bf16 v[80:83], v[176:179], v[218:221], v[80:83]
	v_mfma_f32_16x16x32_bf16 v[68:71], v[168:171], v[226:229], v[68:71]
	v_mfma_f32_16x16x32_bf16 v[64:67], v[176:179], v[226:229], v[64:67]
	v_mfma_f32_16x16x32_bf16 v[116:119], v[172:175], v[206:209], v[116:119]
	v_mfma_f32_16x16x32_bf16 v[112:115], v[194:197], v[206:209], v[112:115]
	v_mfma_f32_16x16x32_bf16 v[100:103], v[172:175], v[214:217], v[100:103]
	v_mfma_f32_16x16x32_bf16 v[96:99], v[194:197], v[214:217], v[96:99]
	v_mfma_f32_16x16x32_bf16 v[84:87], v[172:175], v[222:225], v[84:87]
	v_mfma_f32_16x16x32_bf16 v[80:83], v[194:197], v[222:225], v[80:83]
	v_mfma_f32_16x16x32_bf16 v[68:71], v[172:175], v[230:233], v[68:71]
	v_mfma_f32_16x16x32_bf16 v[64:67], v[194:197], v[230:233], v[64:67]
	s_barrier
	s_add_i32 s15, s15, s2
	v_lshl_add_u64 v[150:151], s[82:83], 0, v[154:155]
	s_mov_b32 m0, s15
	ds_read_b128 v[202:205], v167 offset:16384
	ds_read_b128 v[206:209], v167 offset:17408
	ds_read_b128 v[210:213], v167 offset:18432
	ds_read_b128 v[214:217], v167 offset:19456
	ds_read_b128 v[218:221], v167 offset:20480
	ds_read_b128 v[222:225], v167 offset:21504
	ds_read_b128 v[226:229], v167 offset:22528
	ds_read_b128 v[230:233], v167 offset:23552
	global_load_lds_dwordx4 v[150:151], off
	s_add_i32 m0, s15, 0x2000
	v_lshl_add_u64 v[162:163], s[82:83], 0, v[140:141]
	s_add_u32 s82, s82, s24
	s_addc_u32 s83, s83, s25
	s_add_i32 s14, s14, s2
	global_load_lds_dwordx4 v[162:163], off
	v_lshl_add_u64 v[180:181], s[82:83], 0, v[154:155]
	s_mov_b32 m0, s14
	v_lshl_add_u64 v[234:235], s[82:83], 0, v[140:141]
	global_load_lds_dwordx4 v[180:181], off
	s_add_i32 m0, s14, 0x2000
	v_lshl_add_u64 v[236:237], s[0:1], 0, v[136:137]
	global_load_lds_dwordx4 v[234:235], off
	s_mov_b32 m0, s3
	v_lshl_add_u64 v[238:239], s[0:1], 0, v[138:139]
	global_load_lds_dwordx4 v[236:237], off
	s_mov_b32 m0, s10
	s_nop 0
	global_load_lds_dwordx4 v[238:239], off
	s_waitcnt vmcnt(8)
	s_waitcnt lgkmcnt(0)
	s_barrier
	v_mfma_f32_16x16x32_bf16 v[60:63], v[128:131], v[202:205], v[60:63]
	v_mfma_f32_16x16x32_bf16 v[56:59], v[146:149], v[202:205], v[56:59]
	v_mfma_f32_16x16x32_bf16 v[44:47], v[128:131], v[210:213], v[44:47]
	v_mfma_f32_16x16x32_bf16 v[40:43], v[146:149], v[210:213], v[40:43]
	v_mfma_f32_16x16x32_bf16 v[28:31], v[128:131], v[218:221], v[28:31]
	v_mfma_f32_16x16x32_bf16 v[24:27], v[146:149], v[218:221], v[24:27]
	v_mfma_f32_16x16x32_bf16 v[12:15], v[128:131], v[226:229], v[12:15]
	v_mfma_f32_16x16x32_bf16 v[8:11], v[146:149], v[226:229], v[8:11]
	v_mfma_f32_16x16x32_bf16 v[60:63], v[132:135], v[206:209], v[60:63]
	v_mfma_f32_16x16x32_bf16 v[56:59], v[158:161], v[206:209], v[56:59]
	v_mfma_f32_16x16x32_bf16 v[44:47], v[132:135], v[214:217], v[44:47]
	v_mfma_f32_16x16x32_bf16 v[40:43], v[158:161], v[214:217], v[40:43]
	v_mfma_f32_16x16x32_bf16 v[28:31], v[132:135], v[222:225], v[28:31]
	v_mfma_f32_16x16x32_bf16 v[24:27], v[158:161], v[222:225], v[24:27]
	v_mfma_f32_16x16x32_bf16 v[12:15], v[132:135], v[230:233], v[12:15]
	v_mfma_f32_16x16x32_bf16 v[8:11], v[158:161], v[230:233], v[8:11]
	v_mfma_f32_16x16x32_bf16 v[52:55], v[168:171], v[202:205], v[52:55]
	v_mfma_f32_16x16x32_bf16 v[48:51], v[176:179], v[202:205], v[48:51]
	v_mfma_f32_16x16x32_bf16 v[36:39], v[168:171], v[210:213], v[36:39]
	v_mfma_f32_16x16x32_bf16 v[32:35], v[176:179], v[210:213], v[32:35]
	v_mfma_f32_16x16x32_bf16 v[20:23], v[168:171], v[218:221], v[20:23]
	v_mfma_f32_16x16x32_bf16 v[16:19], v[176:179], v[218:221], v[16:19]
	v_mfma_f32_16x16x32_bf16 v[4:7], v[168:171], v[226:229], v[4:7]
	v_mfma_f32_16x16x32_bf16 v[0:3], v[176:179], v[226:229], v[0:3]
	v_mfma_f32_16x16x32_bf16 v[52:55], v[172:175], v[206:209], v[52:55]
	v_mfma_f32_16x16x32_bf16 v[48:51], v[194:197], v[206:209], v[48:51]
	v_mfma_f32_16x16x32_bf16 v[36:39], v[172:175], v[214:217], v[36:39]
	v_mfma_f32_16x16x32_bf16 v[32:35], v[194:197], v[214:217], v[32:35]
	v_mfma_f32_16x16x32_bf16 v[20:23], v[172:175], v[222:225], v[20:23]
	v_mfma_f32_16x16x32_bf16 v[16:19], v[194:197], v[222:225], v[16:19]
	v_mfma_f32_16x16x32_bf16 v[4:7], v[172:175], v[230:233], v[4:7]
	v_mfma_f32_16x16x32_bf16 v[0:3], v[194:197], v[230:233], v[0:3]
	s_barrier
	s_add_i32 s14, 0, 0x18000
	s_add_i32 s15, 0, 0x1c000
	v_add_u32_e32 v158, s14, v165
	v_add_u32_e32 v193, s15, v165
	ds_read_b128 v[128:131], v158
	ds_read_b128 v[132:135], v158 offset:1024
	ds_read_b128 v[146:149], v158 offset:2048
	ds_read_b128 v[158:161], v158 offset:3072
	ds_read_b128 v[168:171], v193
	ds_read_b128 v[172:175], v193 offset:1024
	ds_read_b128 v[176:179], v193 offset:2048
	ds_read_b128 v[194:197], v193 offset:3072
	s_add_u32 s0, s0, s8
	s_addc_u32 s1, s1, s9
	s_mov_b32 m0, s11
	v_lshl_add_u64 v[240:241], s[0:1], 0, v[136:137]
	ds_read_b128 v[202:205], v167 offset:32768
	ds_read_b128 v[206:209], v167 offset:33792
	ds_read_b128 v[210:213], v167 offset:34816
	ds_read_b128 v[214:217], v167 offset:35840
	ds_read_b128 v[218:221], v167 offset:36864
	ds_read_b128 v[222:225], v167 offset:37888
	ds_read_b128 v[226:229], v167 offset:38912
	ds_read_b128 v[230:233], v167 offset:39936
	global_load_lds_dwordx4 v[240:241], off
	v_lshl_add_u64 v[240:241], s[0:1], 0, v[138:139]
	s_mov_b32 m0, s13
	s_nop 0
	global_load_lds_dwordx4 v[240:241], off
	s_waitcnt vmcnt(8)
	s_waitcnt lgkmcnt(0)
	s_barrier
	v_mfma_f32_16x16x32_bf16 v[124:127], v[128:131], v[202:205], v[124:127]
	v_mfma_f32_16x16x32_bf16 v[120:123], v[146:149], v[202:205], v[120:123]
	v_mfma_f32_16x16x32_bf16 v[108:111], v[128:131], v[210:213], v[108:111]
	v_mfma_f32_16x16x32_bf16 v[104:107], v[146:149], v[210:213], v[104:107]
	v_mfma_f32_16x16x32_bf16 v[92:95], v[128:131], v[218:221], v[92:95]
	v_mfma_f32_16x16x32_bf16 v[88:91], v[146:149], v[218:221], v[88:91]
	v_mfma_f32_16x16x32_bf16 v[76:79], v[128:131], v[226:229], v[76:79]
	v_mfma_f32_16x16x32_bf16 v[72:75], v[146:149], v[226:229], v[72:75]
	v_mfma_f32_16x16x32_bf16 v[124:127], v[132:135], v[206:209], v[124:127]
	v_mfma_f32_16x16x32_bf16 v[120:123], v[158:161], v[206:209], v[120:123]
	v_mfma_f32_16x16x32_bf16 v[108:111], v[132:135], v[214:217], v[108:111]
	v_mfma_f32_16x16x32_bf16 v[104:107], v[158:161], v[214:217], v[104:107]
	v_mfma_f32_16x16x32_bf16 v[92:95], v[132:135], v[222:225], v[92:95]
	v_mfma_f32_16x16x32_bf16 v[88:91], v[158:161], v[222:225], v[88:91]
	v_mfma_f32_16x16x32_bf16 v[76:79], v[132:135], v[230:233], v[76:79]
	v_mfma_f32_16x16x32_bf16 v[72:75], v[158:161], v[230:233], v[72:75]
	v_mfma_f32_16x16x32_bf16 v[116:119], v[168:171], v[202:205], v[116:119]
	v_mfma_f32_16x16x32_bf16 v[112:115], v[176:179], v[202:205], v[112:115]
	v_mfma_f32_16x16x32_bf16 v[100:103], v[168:171], v[210:213], v[100:103]
	v_mfma_f32_16x16x32_bf16 v[96:99], v[176:179], v[210:213], v[96:99]
	v_mfma_f32_16x16x32_bf16 v[84:87], v[168:171], v[218:221], v[84:87]
	v_mfma_f32_16x16x32_bf16 v[80:83], v[176:179], v[218:221], v[80:83]
	v_mfma_f32_16x16x32_bf16 v[68:71], v[168:171], v[226:229], v[68:71]
	v_mfma_f32_16x16x32_bf16 v[64:67], v[176:179], v[226:229], v[64:67]
	v_mfma_f32_16x16x32_bf16 v[116:119], v[172:175], v[206:209], v[116:119]
	v_mfma_f32_16x16x32_bf16 v[112:115], v[194:197], v[206:209], v[112:115]
	v_mfma_f32_16x16x32_bf16 v[100:103], v[172:175], v[214:217], v[100:103]
	v_mfma_f32_16x16x32_bf16 v[96:99], v[194:197], v[214:217], v[96:99]
	v_mfma_f32_16x16x32_bf16 v[84:87], v[172:175], v[222:225], v[84:87]
	v_mfma_f32_16x16x32_bf16 v[80:83], v[194:197], v[222:225], v[80:83]
	v_mfma_f32_16x16x32_bf16 v[68:71], v[172:175], v[230:233], v[68:71]
	v_mfma_f32_16x16x32_bf16 v[64:67], v[194:197], v[230:233], v[64:67]
	s_barrier
	s_add_i32 s0, s14, s2
	v_lshl_add_u64 v[150:151], v[150:151], 0, s[36:37]
	s_mov_b32 m0, s0
	ds_read_b128 v[202:205], v167 offset:49152
	ds_read_b128 v[206:209], v167 offset:50176
	ds_read_b128 v[210:213], v167 offset:51200
	ds_read_b128 v[214:217], v167 offset:52224
	ds_read_b128 v[218:221], v167 offset:53248
	ds_read_b128 v[222:225], v167 offset:54272
	ds_read_b128 v[226:229], v167 offset:55296
	ds_read_b128 v[230:233], v167 offset:56320
	global_load_lds_dwordx4 v[150:151], off
	v_lshl_add_u64 v[150:151], v[162:163], 0, s[36:37]
	s_add_i32 m0, s0, 0x2000
	s_add_i32 s0, s15, s2
	global_load_lds_dwordx4 v[150:151], off
	v_lshl_add_u64 v[150:151], v[180:181], 0, s[36:37]
	s_mov_b32 m0, s0
	s_nop 0
	global_load_lds_dwordx4 v[150:151], off
	v_lshl_add_u64 v[150:151], v[234:235], 0, s[36:37]
	s_add_i32 m0, s0, 0x2000
	s_nop 0
	global_load_lds_dwordx4 v[150:151], off
	v_lshl_add_u64 v[150:151], v[236:237], 0, s[36:37]
	s_mov_b32 m0, s18
	s_nop 0
	global_load_lds_dwordx4 v[150:151], off
	v_lshl_add_u64 v[150:151], v[238:239], 0, s[36:37]
	s_mov_b32 m0, s28
	s_nop 0
	global_load_lds_dwordx4 v[150:151], off
	s_waitcnt vmcnt(8)
	s_waitcnt lgkmcnt(0)
	s_barrier
	v_mfma_f32_16x16x32_bf16 v[60:63], v[128:131], v[202:205], v[60:63]
	v_mfma_f32_16x16x32_bf16 v[56:59], v[146:149], v[202:205], v[56:59]
	v_mfma_f32_16x16x32_bf16 v[44:47], v[128:131], v[210:213], v[44:47]
	v_mfma_f32_16x16x32_bf16 v[40:43], v[146:149], v[210:213], v[40:43]
	v_mfma_f32_16x16x32_bf16 v[28:31], v[128:131], v[218:221], v[28:31]
	v_mfma_f32_16x16x32_bf16 v[24:27], v[146:149], v[218:221], v[24:27]
	v_mfma_f32_16x16x32_bf16 v[12:15], v[128:131], v[226:229], v[12:15]
	v_mfma_f32_16x16x32_bf16 v[8:11], v[146:149], v[226:229], v[8:11]
	v_mfma_f32_16x16x32_bf16 v[60:63], v[132:135], v[206:209], v[60:63]
	v_mfma_f32_16x16x32_bf16 v[56:59], v[158:161], v[206:209], v[56:59]
	v_mfma_f32_16x16x32_bf16 v[44:47], v[132:135], v[214:217], v[44:47]
	v_mfma_f32_16x16x32_bf16 v[40:43], v[158:161], v[214:217], v[40:43]
	v_mfma_f32_16x16x32_bf16 v[28:31], v[132:135], v[222:225], v[28:31]
	v_mfma_f32_16x16x32_bf16 v[24:27], v[158:161], v[222:225], v[24:27]
	v_mfma_f32_16x16x32_bf16 v[12:15], v[132:135], v[230:233], v[12:15]
	v_mfma_f32_16x16x32_bf16 v[8:11], v[158:161], v[230:233], v[8:11]
	v_mfma_f32_16x16x32_bf16 v[52:55], v[168:171], v[202:205], v[52:55]
	v_mfma_f32_16x16x32_bf16 v[48:51], v[176:179], v[202:205], v[48:51]
	v_mfma_f32_16x16x32_bf16 v[36:39], v[168:171], v[210:213], v[36:39]
	v_mfma_f32_16x16x32_bf16 v[32:35], v[176:179], v[210:213], v[32:35]
	v_mfma_f32_16x16x32_bf16 v[20:23], v[168:171], v[218:221], v[20:23]
	v_mfma_f32_16x16x32_bf16 v[16:19], v[176:179], v[218:221], v[16:19]
	v_mfma_f32_16x16x32_bf16 v[4:7], v[168:171], v[226:229], v[4:7]
	v_mfma_f32_16x16x32_bf16 v[0:3], v[176:179], v[226:229], v[0:3]
	v_mfma_f32_16x16x32_bf16 v[52:55], v[172:175], v[206:209], v[52:55]
	v_mfma_f32_16x16x32_bf16 v[48:51], v[194:197], v[206:209], v[48:51]
	v_mfma_f32_16x16x32_bf16 v[36:39], v[172:175], v[214:217], v[36:39]
	v_mfma_f32_16x16x32_bf16 v[32:35], v[194:197], v[214:217], v[32:35]
	v_mfma_f32_16x16x32_bf16 v[20:23], v[172:175], v[222:225], v[20:23]
	v_mfma_f32_16x16x32_bf16 v[16:19], v[194:197], v[222:225], v[16:19]
	v_mfma_f32_16x16x32_bf16 v[4:7], v[172:175], v[230:233], v[4:7]
	v_mfma_f32_16x16x32_bf16 v[0:3], v[194:197], v[230:233], v[0:3]
	s_barrier
	s_add_u32 s42, s42, 0x100
	s_addc_u32 s43, s43, 0
	s_add_u32 s44, s44, 0x100
	s_addc_u32 s45, s45, 0
	s_cmp_ge_u32 s47, s31
	s_mov_b32 s0, s47
	s_cbranch_scc0 .LBB0_482
	s_and_b64 vcc, exec, s[66:67]
	s_cbranch_vccz .LBB0_485
	s_barrier
